# attention tile loops (pass A/B): counted vmcnt keeps the two-tiles-ahead K/V prefetch in flight on the common path (uniform state word in s32), full drain only on the last tiles
# baseline (speedup 1.0000x reference)
_Z6mk_fwd5KArgs:
	s_mov_b32 s32, 0
	s_mov_b32 s88, s2
	s_load_dwordx2 s[2:3], s[0:1], 0xc0
	s_load_dword s90, s[0:1], 0xc8
	v_readfirstlane_b32 s6, v0
	s_waitcnt lgkmcnt(0)
	v_writelane_b32 v253, s2, 0
	s_nop 1
	v_writelane_b32 v253, s3, 1
	s_add_u32 s2, s0, 0xc8
	s_addc_u32 s3, s1, 0
	v_writelane_b32 v253, s2, 2
	s_nop 1
	v_writelane_b32 v253, s3, 3
	s_movk_i32 s2, 0x80
	v_cmp_gt_u32_e32 vcc, s2, v0
	s_and_saveexec_b64 s[2:3], vcc
	v_lshl_add_u32 v1, v0, 2, 0
	v_add_u32_e32 v1, 0x26000, v1
	v_mov_b32_e32 v2, 0
	ds_write_b32 v1, v2
	s_or_b64 exec, exec, s[2:3]
	s_load_dwordx2 s[2:3], s[0:1], 0xc0
	s_waitcnt lgkmcnt(0)
	s_barrier
	v_cmp_eq_u32_e64 s[4:5], 0, v0
	s_add_u32 s2, s2, 0x4000
	s_addc_u32 s3, s3, 0
	v_writelane_b32 v253, s2, 4
	s_nop 1
	v_writelane_b32 v253, s3, 5
	s_getreg_b32 s2, hwreg(HW_REG_XCC_ID, 0, 4)
	s_and_b32 s2, s2, 15
	v_writelane_b32 v253, s2, 6
	s_mov_b64 s[2:3], exec
	v_writelane_b32 v253, s4, 7
	s_nop 1
	v_writelane_b32 v253, s5, 8
	s_and_b64 s[4:5], s[2:3], s[4:5]
	s_mov_b64 exec, s[4:5]
	s_cbranch_execz .LBB0_5
	s_mov_b64 s[4:5], exec
	v_mbcnt_lo_u32_b32 v1, s4, 0
	v_mbcnt_hi_u32_b32 v1, s5, v1
	v_cmp_eq_u32_e32 vcc, 0, v1
	s_and_b64 s[8:9], exec, vcc
	s_mov_b64 exec, s[8:9]
	s_cbranch_execz .LBB0_5
	v_readlane_b32 s7, v253, 6
	s_bcnt1_i32_b64 s4, s[4:5]
	s_lshl_b32 s7, s7, 8
	v_mov_b32_e32 v2, s4
	v_readlane_b32 s4, v253, 4
	v_mov_b32_e32 v1, s7
	v_readlane_b32 s5, v253, 5
	s_nop 4
	global_atomic_add v1, v2, s[4:5] offset:1024

.LBB0_753:
	s_add_i32 s5, s4, -1
	v_add_u32_e32 v166, v140, v152
	s_cmp_eq_u32 s32, 1
	s_cbranch_scc0 .Latw_cons_0
	s_cmp_le_i32 s5, s12
	s_waitcnt vmcnt(8)
	ds_write_b128 v166, v[68:71]
	ds_write_b128 v166, v[72:75] offset:4608
	ds_write_b128 v166, v[76:79] offset:1152
	ds_write_b128 v166, v[80:83] offset:5760
	ds_write_b128 v166, v[84:87] offset:2304
	ds_write_b128 v166, v[88:91] offset:6912
	ds_write_b128 v166, v[104:107] offset:3456
	ds_write_b128 v166, v[108:111] offset:8064
	s_branch .Latw_pa_0
.Latw_cons_0:
	s_cmp_le_i32 s5, s12
	s_waitcnt vmcnt(0)
	ds_write_b128 v166, v[68:71]
	ds_write_b128 v166, v[72:75] offset:4608
	ds_write_b128 v166, v[76:79] offset:1152
	ds_write_b128 v166, v[80:83] offset:5760
	ds_write_b128 v166, v[84:87] offset:2304
	ds_write_b128 v166, v[88:91] offset:6912
	ds_write_b128 v166, v[104:107] offset:3456
	ds_write_b128 v166, v[108:111] offset:8064
.Latw_pa_0:
	s_mov_b32 s32, 0
	s_cbranch_scc0 .LBB0_755
	v_subrev_u32_e32 v36, 32, v160
	v_min_i32_e32 v36, 0x7ff, v36
	v_ashrrev_i32_e32 v37, 31, v36
	v_lshlrev_b64 v[36:37], 11, v[36:37]
	v_lshl_add_u64 v[36:37], v[36:37], 0, v[2:3]
	v_lshl_add_u64 v[38:39], s[0:1], 0, v[36:37]
	v_lshl_add_u64 v[36:37], s[72:73], 0, v[36:37]
	global_load_dwordx4 v[68:71], v[38:39], off
	global_load_dwordx4 v[72:75], v[36:37], off
	v_subrev_u32_e32 v36, 24, v160
	v_min_i32_e32 v36, 0x7ff, v36
	v_ashrrev_i32_e32 v37, 31, v36
	v_lshlrev_b64 v[36:37], 11, v[36:37]
	v_lshl_add_u64 v[36:37], v[36:37], 0, v[2:3]
	v_lshl_add_u64 v[38:39], s[0:1], 0, v[36:37]
	v_lshl_add_u64 v[36:37], s[72:73], 0, v[36:37]
	global_load_dwordx4 v[76:79], v[38:39], off
	global_load_dwordx4 v[80:83], v[36:37], off
	v_add_u32_e32 v36, -16, v160
	v_min_i32_e32 v36, 0x7ff, v36
	v_ashrrev_i32_e32 v37, 31, v36
	v_lshlrev_b64 v[36:37], 11, v[36:37]
	v_lshl_add_u64 v[36:37], v[36:37], 0, v[2:3]
	v_lshl_add_u64 v[38:39], s[0:1], 0, v[36:37]
	v_lshl_add_u64 v[36:37], s[72:73], 0, v[36:37]
	global_load_dwordx4 v[84:87], v[38:39], off
	global_load_dwordx4 v[88:91], v[36:37], off
	v_add_u32_e32 v36, -8, v160
	v_min_i32_e32 v36, 0x7ff, v36
	v_ashrrev_i32_e32 v37, 31, v36
	v_lshlrev_b64 v[36:37], 11, v[36:37]
	v_lshl_add_u64 v[36:37], v[36:37], 0, v[2:3]
	v_lshl_add_u64 v[38:39], s[0:1], 0, v[36:37]
	v_lshl_add_u64 v[36:37], s[72:73], 0, v[36:37]
	global_load_dwordx4 v[104:107], v[38:39], off
	global_load_dwordx4 v[108:111], v[36:37], off
	s_mov_b32 s32, 2

.LBB0_757:
	v_sub_f32_e32 v138, v165, v51
	v_exp_f32_e32 v138, v138
	v_sub_f32_e32 v37, v37, v51
	v_exp_f32_e32 v37, v37
	v_sub_f32_e32 v38, v38, v51
	v_exp_f32_e32 v38, v38
	v_sub_f32_e32 v39, v39, v51
	v_exp_f32_e32 v39, v39
	v_sub_f32_e32 v40, v40, v51
	v_add_f32_e32 v165, 0, v138
	v_exp_f32_e32 v40, v40
	v_sub_f32_e32 v41, v41, v51
	v_add_f32_e32 v165, v37, v165
	v_exp_f32_e32 v41, v41
	v_sub_f32_e32 v42, v42, v51
	v_add_f32_e32 v165, v38, v165
	v_exp_f32_e32 v42, v42
	v_sub_f32_e32 v43, v43, v51
	v_add_f32_e32 v165, v39, v165
	v_exp_f32_e32 v43, v43
	v_sub_f32_e32 v44, v44, v51
	v_add_f32_e32 v165, v40, v165
	v_exp_f32_e32 v44, v44
	v_sub_f32_e32 v45, v45, v51
	v_add_f32_e32 v165, v41, v165
	v_exp_f32_e32 v45, v45
	v_sub_f32_e32 v46, v46, v51
	v_add_f32_e32 v165, v42, v165
	v_exp_f32_e32 v46, v46
	v_sub_f32_e32 v168, v168, v51
	v_add_f32_e32 v165, v43, v165
	v_exp_f32_e32 v168, v168
	v_sub_f32_e32 v47, v47, v51
	v_add_f32_e32 v165, v44, v165
	v_exp_f32_e32 v47, v47
	v_sub_f32_e32 v48, v48, v51
	v_add_f32_e32 v165, v45, v165
	v_exp_f32_e32 v48, v48
	v_sub_f32_e32 v49, v49, v51
	v_add_f32_e32 v165, v46, v165
	v_exp_f32_e32 v49, v49
	v_sub_f32_e32 v50, v50, v51
	v_add_f32_e32 v165, v168, v165
	v_exp_f32_e32 v50, v50
	v_add_f32_e32 v165, v47, v165
	v_add_f32_e32 v165, v48, v165
	v_add_f32_e32 v165, v49, v165
	v_add_f32_e32 v165, v50, v165
	v_fmac_f32_e32 v165, v163, v36
	v_cvt_pk_bf16_f32 v36, v138, v37
	v_cvt_pk_bf16_f32 v37, v38, v39
	v_cvt_pk_bf16_f32 v38, v40, v41
	v_cvt_pk_bf16_f32 v39, v42, v43
	v_cvt_pk_bf16_f32 v40, v44, v45
	v_cvt_pk_bf16_f32 v41, v46, v168
	v_cvt_pk_bf16_f32 v42, v47, v48
	ds_read_b64_tr_b16 v[44:45], v162 offset:4608
	ds_read_b64_tr_b16 v[46:47], v162 offset:5760
	s_waitcnt lgkmcnt(0)
	v_mfma_f32_32x32x16_bf16 v[4:19], v[44:47], v[36:39], v[4:19]
	ds_read_b64_tr_b16 v[44:45], v162 offset:4672
	ds_read_b64_tr_b16 v[46:47], v162 offset:5824
	v_cvt_pk_bf16_f32 v43, v49, v50
	s_add_i32 s6, s4, -3
	s_cmp_ge_i32 s6, s12
	s_waitcnt lgkmcnt(0)
	v_mfma_f32_32x32x16_bf16 v[20:35], v[44:47], v[36:39], v[20:35]
	ds_read_b64_tr_b16 v[36:37], v162 offset:6912
	ds_read_b64_tr_b16 v[38:39], v162 offset:8064
	s_waitcnt lgkmcnt(0)
	v_mfma_f32_32x32x16_bf16 v[4:19], v[36:39], v[40:43], v[4:19]
	ds_read_b64_tr_b16 v[36:37], v162 offset:6976
	ds_read_b64_tr_b16 v[38:39], v162 offset:8128
	s_waitcnt lgkmcnt(0)
	v_mfma_f32_32x32x16_bf16 v[20:35], v[36:39], v[40:43], v[20:35]
	s_cbranch_scc1 .LBB0_751
	s_waitcnt vmcnt(8)
	s_cmp_eq_u32 s32, 2
	s_cbranch_scc1 .Latw_pb_0
	s_waitcnt vmcnt(0)
.Latw_pb_0:
	s_cmp_gt_i32 s4, s12
	ds_write_b128 v166, v[92:95]
	ds_write_b128 v166, v[96:99] offset:4608
	ds_write_b128 v166, v[100:103] offset:1152
	ds_write_b128 v166, v[112:115] offset:5760
	ds_write_b128 v166, v[116:119] offset:2304
	ds_write_b128 v166, v[120:123] offset:6912
	ds_write_b128 v166, v[124:127] offset:3456
	ds_write_b128 v166, v[128:131] offset:8064
	s_mov_b32 s32, 0
	s_cbranch_scc1 .LBB0_760
	v_min_i32_e32 v36, 0x7ff, v160
	v_ashrrev_i32_e32 v37, 31, v36
	v_lshlrev_b64 v[36:37], 11, v[36:37]
	v_lshl_add_u64 v[36:37], v[36:37], 0, v[2:3]
	v_lshl_add_u64 v[38:39], s[0:1], 0, v[36:37]
	v_lshl_add_u64 v[36:37], s[72:73], 0, v[36:37]
	global_load_dwordx4 v[92:95], v[38:39], off
	global_load_dwordx4 v[96:99], v[36:37], off
	v_add_u32_e32 v36, 8, v160
	v_min_i32_e32 v36, 0x7ff, v36
	v_ashrrev_i32_e32 v37, 31, v36
	v_lshlrev_b64 v[36:37], 11, v[36:37]
	v_lshl_add_u64 v[36:37], v[36:37], 0, v[2:3]
	v_lshl_add_u64 v[38:39], s[0:1], 0, v[36:37]
	v_lshl_add_u64 v[36:37], s[72:73], 0, v[36:37]
	global_load_dwordx4 v[100:103], v[38:39], off
	global_load_dwordx4 v[112:115], v[36:37], off
	v_add_u32_e32 v36, 16, v160
	v_min_i32_e32 v36, 0x7ff, v36
	v_ashrrev_i32_e32 v37, 31, v36
	v_lshlrev_b64 v[36:37], 11, v[36:37]
	v_lshl_add_u64 v[36:37], v[36:37], 0, v[2:3]
	v_lshl_add_u64 v[38:39], s[0:1], 0, v[36:37]
	v_lshl_add_u64 v[36:37], s[72:73], 0, v[36:37]
	global_load_dwordx4 v[116:119], v[38:39], off
	global_load_dwordx4 v[120:123], v[36:37], off
	v_add_u32_e32 v36, 24, v160
	v_min_i32_e32 v36, 0x7ff, v36
	v_ashrrev_i32_e32 v37, 31, v36
	v_lshlrev_b64 v[36:37], 11, v[36:37]
	v_lshl_add_u64 v[36:37], v[36:37], 0, v[2:3]
	v_lshl_add_u64 v[38:39], s[0:1], 0, v[36:37]
	v_lshl_add_u64 v[36:37], s[72:73], 0, v[36:37]
	global_load_dwordx4 v[124:127], v[38:39], off
	global_load_dwordx4 v[128:131], v[36:37], off
	s_mov_b32 s32, 1

.LBB0_781:
	s_add_i32 s11, s10, -1
	v_add_u32_e32 v160, v141, v143
	v_add_u32_e32 v161, v141, v145
	v_add_u32_e32 v163, v141, v148
	v_add_u32_e32 v162, v141, v150
	s_cmp_eq_u32 s32, 1
	s_cbranch_scc0 .Latw_cons_1
	s_cmp_le_i32 s11, s15
	s_waitcnt vmcnt(15)
	ds_write_b128 v160, v[68:71]
	s_waitcnt vmcnt(14)
	ds_write_b128 v160, v[72:75] offset:4608
	s_waitcnt vmcnt(13)
	ds_write_b128 v161, v[76:79]
	s_waitcnt vmcnt(12)
	ds_write_b128 v161, v[80:83] offset:4608
	s_waitcnt vmcnt(11)
	ds_write_b128 v163, v[84:87]
	s_waitcnt vmcnt(10)
	ds_write_b128 v163, v[92:95] offset:4608
	s_waitcnt vmcnt(9)
	ds_write_b128 v162, v[104:107]
	s_waitcnt vmcnt(8)
	ds_write_b128 v162, v[108:111] offset:4608
	s_branch .Latw_pa_1
.Latw_cons_1:
	s_cmp_le_i32 s11, s15
	s_waitcnt vmcnt(7)
	ds_write_b128 v160, v[68:71]
	s_waitcnt vmcnt(6)
	ds_write_b128 v160, v[72:75] offset:4608
	s_waitcnt vmcnt(5)
	ds_write_b128 v161, v[76:79]
	s_waitcnt vmcnt(4)
	ds_write_b128 v161, v[80:83] offset:4608
	s_waitcnt vmcnt(3)
	ds_write_b128 v163, v[84:87]
	s_waitcnt vmcnt(2)
	ds_write_b128 v163, v[92:95] offset:4608
	s_waitcnt vmcnt(1)
	ds_write_b128 v162, v[104:107]
	s_waitcnt vmcnt(0)
	ds_write_b128 v162, v[108:111] offset:4608
.Latw_pa_1:
	s_mov_b32 s32, 0
	s_cbranch_scc0 .LBB0_783
	v_subrev_u32_e32 v36, 32, v137
	v_min_i32_e32 v36, 0x7ff, v36
	v_ashrrev_i32_e32 v37, 31, v36
	v_lshlrev_b64 v[36:37], 11, v[36:37]
	v_lshl_add_u64 v[36:37], v[36:37], 0, v[134:135]
	v_lshl_add_u64 v[38:39], s[0:1], 0, v[36:37]
	v_lshl_add_u64 v[36:37], s[72:73], 0, v[36:37]
	global_load_dwordx4 v[68:71], v[38:39], off
	global_load_dwordx4 v[72:75], v[36:37], off
	v_subrev_u32_e32 v36, 24, v137
	v_min_i32_e32 v36, 0x7ff, v36
	v_ashrrev_i32_e32 v37, 31, v36
	v_lshlrev_b64 v[36:37], 11, v[36:37]
	v_lshl_add_u64 v[36:37], v[36:37], 0, v[134:135]
	v_lshl_add_u64 v[38:39], s[0:1], 0, v[36:37]
	v_lshl_add_u64 v[36:37], s[72:73], 0, v[36:37]
	global_load_dwordx4 v[76:79], v[38:39], off
	global_load_dwordx4 v[80:83], v[36:37], off
	v_add_u32_e32 v36, -16, v137
	v_min_i32_e32 v36, 0x7ff, v36
	v_ashrrev_i32_e32 v37, 31, v36
	v_lshlrev_b64 v[36:37], 11, v[36:37]
	v_lshl_add_u64 v[36:37], v[36:37], 0, v[134:135]
	v_lshl_add_u64 v[38:39], s[0:1], 0, v[36:37]
	v_lshl_add_u64 v[36:37], s[72:73], 0, v[36:37]
	global_load_dwordx4 v[84:87], v[38:39], off
	global_load_dwordx4 v[92:95], v[36:37], off
	v_add_u32_e32 v36, -8, v137
	v_min_i32_e32 v36, 0x7ff, v36
	v_ashrrev_i32_e32 v37, 31, v36
	v_lshlrev_b64 v[36:37], 11, v[36:37]
	v_lshl_add_u64 v[36:37], v[36:37], 0, v[134:135]
	v_lshl_add_u64 v[38:39], s[0:1], 0, v[36:37]
	v_lshl_add_u64 v[36:37], s[72:73], 0, v[36:37]
	global_load_dwordx4 v[104:107], v[38:39], off
	global_load_dwordx4 v[108:111], v[36:37], off
	s_mov_b32 s32, 2

.LBB0_785:
	v_sub_f32_e32 v136, v164, v51
	v_exp_f32_e32 v136, v136
	v_sub_f32_e32 v37, v37, v51
	v_exp_f32_e32 v37, v37
	v_sub_f32_e32 v38, v38, v51
	v_exp_f32_e32 v38, v38
	v_sub_f32_e32 v39, v39, v51
	v_exp_f32_e32 v39, v39
	v_sub_f32_e32 v40, v40, v51
	v_add_f32_e32 v164, 0, v136
	v_exp_f32_e32 v40, v40
	v_sub_f32_e32 v41, v41, v51
	v_add_f32_e32 v164, v37, v164
	v_exp_f32_e32 v41, v41
	v_sub_f32_e32 v42, v42, v51
	v_add_f32_e32 v164, v38, v164
	v_exp_f32_e32 v42, v42
	v_sub_f32_e32 v43, v43, v51
	v_add_f32_e32 v164, v39, v164
	v_exp_f32_e32 v43, v43
	v_sub_f32_e32 v44, v44, v51
	v_add_f32_e32 v164, v40, v164
	v_exp_f32_e32 v44, v44
	v_sub_f32_e32 v45, v45, v51
	v_add_f32_e32 v164, v41, v164
	v_exp_f32_e32 v45, v45
	v_sub_f32_e32 v46, v46, v51
	v_add_f32_e32 v164, v42, v164
	v_exp_f32_e32 v46, v46
	v_sub_f32_e32 v165, v165, v51
	v_add_f32_e32 v164, v43, v164
	v_exp_f32_e32 v165, v165
	v_sub_f32_e32 v47, v47, v51
	v_add_f32_e32 v164, v44, v164
	v_exp_f32_e32 v47, v47
	v_sub_f32_e32 v48, v48, v51
	v_add_f32_e32 v164, v45, v164
	v_exp_f32_e32 v48, v48
	v_sub_f32_e32 v49, v49, v51
	v_add_f32_e32 v164, v46, v164
	v_exp_f32_e32 v49, v49
	v_sub_f32_e32 v50, v50, v51
	v_add_f32_e32 v164, v165, v164
	v_exp_f32_e32 v50, v50
	v_add_f32_e32 v164, v47, v164
	v_add_f32_e32 v164, v48, v164
	v_add_f32_e32 v164, v49, v164
	v_add_f32_e32 v164, v50, v164
	v_fmac_f32_e32 v164, v158, v36
	v_cvt_pk_bf16_f32 v36, v136, v37
	v_cvt_pk_bf16_f32 v37, v38, v39
	v_cvt_pk_bf16_f32 v38, v40, v41
	v_cvt_pk_bf16_f32 v39, v42, v43
	v_cvt_pk_bf16_f32 v40, v44, v45
	v_cvt_pk_bf16_f32 v41, v46, v165
	v_cvt_pk_bf16_f32 v42, v47, v48
	ds_read_b64_tr_b16 v[44:45], v156 offset:4608
	ds_read_b64_tr_b16 v[46:47], v156 offset:5760
	s_waitcnt lgkmcnt(0)
	v_mfma_f32_32x32x16_bf16 v[4:19], v[44:47], v[36:39], v[4:19]
	ds_read_b64_tr_b16 v[44:45], v156 offset:4672
	ds_read_b64_tr_b16 v[46:47], v156 offset:5824
	v_cvt_pk_bf16_f32 v43, v49, v50
	s_add_i32 s16, s10, -3
	s_cmp_ge_i32 s16, s15
	s_waitcnt lgkmcnt(0)
	v_mfma_f32_32x32x16_bf16 v[20:35], v[44:47], v[36:39], v[20:35]
	ds_read_b64_tr_b16 v[36:37], v156 offset:6912
	ds_read_b64_tr_b16 v[38:39], v156 offset:8064
	s_waitcnt lgkmcnt(0)
	v_mfma_f32_32x32x16_bf16 v[4:19], v[36:39], v[40:43], v[4:19]
	ds_read_b64_tr_b16 v[36:37], v156 offset:6976
	ds_read_b64_tr_b16 v[38:39], v156 offset:8128
	s_waitcnt lgkmcnt(0)
	v_mfma_f32_32x32x16_bf16 v[20:35], v[36:39], v[40:43], v[20:35]
	s_cbranch_scc1 .LBB0_779
	s_waitcnt vmcnt(8)
	s_cmp_eq_u32 s32, 2
	s_cbranch_scc1 .Latw_pb_1
	s_waitcnt vmcnt(0)
.Latw_pb_1:
	s_cmp_gt_i32 s10, s15
	ds_write_b128 v160, v[88:91]
	ds_write_b128 v160, v[96:99] offset:4608
	ds_write_b128 v161, v[100:103]
	ds_write_b128 v161, v[112:115] offset:4608
	ds_write_b128 v163, v[116:119]
	ds_write_b128 v163, v[120:123] offset:4608
	ds_write_b128 v162, v[124:127]
	ds_write_b128 v162, v[128:131] offset:4608
	s_mov_b32 s32, 0
	s_cbranch_scc1 .LBB0_788
	v_min_i32_e32 v36, 0x7ff, v137
	v_ashrrev_i32_e32 v37, 31, v36
	v_lshlrev_b64 v[36:37], 11, v[36:37]
	v_lshl_add_u64 v[36:37], v[36:37], 0, v[134:135]
	v_lshl_add_u64 v[38:39], s[0:1], 0, v[36:37]
	v_lshl_add_u64 v[36:37], s[72:73], 0, v[36:37]
	global_load_dwordx4 v[88:91], v[38:39], off
	global_load_dwordx4 v[96:99], v[36:37], off
	v_add_u32_e32 v36, 8, v137
	v_min_i32_e32 v36, 0x7ff, v36
	v_ashrrev_i32_e32 v37, 31, v36
	v_lshlrev_b64 v[36:37], 11, v[36:37]
	v_lshl_add_u64 v[36:37], v[36:37], 0, v[134:135]
	v_lshl_add_u64 v[38:39], s[0:1], 0, v[36:37]
	v_lshl_add_u64 v[36:37], s[72:73], 0, v[36:37]
	global_load_dwordx4 v[100:103], v[38:39], off
	global_load_dwordx4 v[112:115], v[36:37], off
	v_add_u32_e32 v36, 16, v137
	v_min_i32_e32 v36, 0x7ff, v36
	v_ashrrev_i32_e32 v37, 31, v36
	v_lshlrev_b64 v[36:37], 11, v[36:37]
	v_lshl_add_u64 v[36:37], v[36:37], 0, v[134:135]
	v_lshl_add_u64 v[38:39], s[0:1], 0, v[36:37]
	v_lshl_add_u64 v[36:37], s[72:73], 0, v[36:37]
	global_load_dwordx4 v[116:119], v[38:39], off
	global_load_dwordx4 v[120:123], v[36:37], off
	v_add_u32_e32 v36, 24, v137
	v_min_i32_e32 v36, 0x7ff, v36
	v_ashrrev_i32_e32 v37, 31, v36
	v_lshlrev_b64 v[36:37], 11, v[36:37]
	v_lshl_add_u64 v[36:37], v[36:37], 0, v[134:135]
	v_lshl_add_u64 v[38:39], s[0:1], 0, v[36:37]
	v_lshl_add_u64 v[36:37], s[72:73], 0, v[36:37]
	global_load_dwordx4 v[124:127], v[38:39], off
	global_load_dwordx4 v[128:131], v[36:37], off
	s_mov_b32 s32, 1

.LBB0_855:
	s_add_i32 s16, s17, 2
	s_cmp_ge_i32 s17, s14
	s_cselect_b64 s[4:5], -1, 0
	v_add_u32_e32 v177, v143, v155
	s_and_b64 vcc, exec, s[4:5]
	s_cmp_eq_u32 s32, 1
	s_cbranch_scc0 .Latw_cons_2
	s_waitcnt vmcnt(15)
	ds_write_b128 v177, v[68:71]
	s_waitcnt vmcnt(14)
	ds_write_b128 v177, v[72:75] offset:4608
	s_waitcnt vmcnt(13)
	ds_write_b128 v177, v[76:79] offset:1152
	s_waitcnt vmcnt(12)
	ds_write_b128 v177, v[80:83] offset:5760
	s_waitcnt vmcnt(11)
	ds_write_b128 v177, v[84:87] offset:2304
	s_waitcnt vmcnt(10)
	ds_write_b128 v177, v[88:91] offset:6912
	s_waitcnt vmcnt(9)
	ds_write_b128 v177, v[100:103] offset:3456
	s_waitcnt vmcnt(8)
	ds_write_b128 v177, v[104:107] offset:8064
	s_branch .Latw_pa_2
.Latw_cons_2:
	s_waitcnt vmcnt(7)
	ds_write_b128 v177, v[68:71]
	s_waitcnt vmcnt(6)
	ds_write_b128 v177, v[72:75] offset:4608
	s_waitcnt vmcnt(5)
	ds_write_b128 v177, v[76:79] offset:1152
	s_waitcnt vmcnt(4)
	ds_write_b128 v177, v[80:83] offset:5760
	s_waitcnt vmcnt(3)
	ds_write_b128 v177, v[84:87] offset:2304
	s_waitcnt vmcnt(2)
	ds_write_b128 v177, v[88:91] offset:6912
	s_waitcnt vmcnt(1)
	ds_write_b128 v177, v[100:103] offset:3456
	s_waitcnt vmcnt(0)
	ds_write_b128 v177, v[104:107] offset:8064
.Latw_pa_2:
	s_mov_b32 s32, 0
	s_cbranch_vccnz .LBB0_857
	s_cmp_gt_i32 s16, s12
	s_cselect_b32 s19, s13, s11
	s_cselect_b32 s18, 4, 2
	s_add_i32 s19, s19, s17
	s_lshl_b32 s19, s19, 5
	s_add_i32 s19, s19, 64
	s_lshl_b32 s22, -1, s18
	v_or_b32_e32 v40, s19, v144
	s_andn2_b32 s22, s7, s22
	v_lshlrev_b32_e32 v36, s18, v40
	v_add_u32_e32 v36, s22, v36
	v_min_i32_e32 v36, 0x7ff, v36
	v_ashrrev_i32_e32 v37, 31, v36
	v_lshlrev_b64 v[36:37], 11, v[36:37]
	v_lshl_add_u64 v[36:37], v[36:37], 0, v[140:141]
	v_lshl_add_u64 v[38:39], s[0:1], 0, v[36:37]
	v_lshl_add_u64 v[36:37], s[72:73], 0, v[36:37]
	global_load_dwordx4 v[68:71], v[38:39], off
	global_load_dwordx4 v[72:75], v[36:37], off
	v_or_b32_e32 v36, 8, v40
	v_lshlrev_b32_e32 v36, s18, v36
	v_add_u32_e32 v36, s22, v36
	v_min_i32_e32 v36, 0x7ff, v36
	v_ashrrev_i32_e32 v37, 31, v36
	v_lshlrev_b64 v[36:37], 11, v[36:37]
	v_lshl_add_u64 v[36:37], v[36:37], 0, v[140:141]
	v_lshl_add_u64 v[38:39], s[0:1], 0, v[36:37]
	v_lshl_add_u64 v[36:37], s[72:73], 0, v[36:37]
	global_load_dwordx4 v[76:79], v[38:39], off
	global_load_dwordx4 v[80:83], v[36:37], off
	v_or_b32_e32 v36, 16, v40
	v_lshlrev_b32_e32 v36, s18, v36
	v_add_u32_e32 v36, s22, v36
	v_min_i32_e32 v36, 0x7ff, v36
	v_ashrrev_i32_e32 v37, 31, v36
	v_lshlrev_b64 v[36:37], 11, v[36:37]
	v_lshl_add_u64 v[36:37], v[36:37], 0, v[140:141]
	v_lshl_add_u64 v[38:39], s[0:1], 0, v[36:37]
	v_lshl_add_u64 v[36:37], s[72:73], 0, v[36:37]
	global_load_dwordx4 v[84:87], v[38:39], off
	global_load_dwordx4 v[88:91], v[36:37], off
	v_or_b32_e32 v36, 24, v40
	v_lshlrev_b32_e32 v36, s18, v36
	v_add_u32_e32 v36, s22, v36
	v_min_i32_e32 v36, 0x7ff, v36
	v_ashrrev_i32_e32 v37, 31, v36
	v_lshlrev_b64 v[36:37], 11, v[36:37]
	v_lshl_add_u64 v[36:37], v[36:37], 0, v[140:141]
	v_lshl_add_u64 v[38:39], s[0:1], 0, v[36:37]
	v_lshl_add_u64 v[36:37], s[72:73], 0, v[36:37]
	global_load_dwordx4 v[100:103], v[38:39], off
	global_load_dwordx4 v[104:107], v[36:37], off
	s_mov_b32 s32, 2

.LBB0_859:
	v_sub_f32_e32 v49, v178, v48
	v_exp_f32_e32 v49, v49
	v_sub_f32_e32 v37, v37, v48
	v_exp_f32_e32 v37, v37
	v_sub_f32_e32 v38, v38, v48
	v_exp_f32_e32 v38, v38
	v_sub_f32_e32 v39, v39, v48
	v_exp_f32_e32 v39, v39
	v_sub_f32_e32 v40, v40, v48
	v_add_f32_e32 v50, 0, v49
	v_exp_f32_e32 v40, v40
	v_sub_f32_e32 v41, v41, v48
	v_add_f32_e32 v50, v37, v50
	v_exp_f32_e32 v41, v41
	v_sub_f32_e32 v42, v42, v48
	v_add_f32_e32 v50, v38, v50
	v_exp_f32_e32 v42, v42
	v_sub_f32_e32 v43, v43, v48
	v_add_f32_e32 v50, v39, v50
	v_exp_f32_e32 v43, v43
	v_sub_f32_e32 v51, v182, v48
	v_add_f32_e32 v50, v40, v50
	v_exp_f32_e32 v51, v51
	v_sub_f32_e32 v142, v181, v48
	v_add_f32_e32 v50, v41, v50
	v_exp_f32_e32 v142, v142
	v_sub_f32_e32 v178, v180, v48
	v_add_f32_e32 v50, v42, v50
	v_exp_f32_e32 v180, v178
	v_sub_f32_e32 v178, v179, v48
	v_add_f32_e32 v50, v43, v50
	v_exp_f32_e32 v179, v178
	v_sub_f32_e32 v44, v44, v48
	v_add_f32_e32 v50, v51, v50
	v_exp_f32_e32 v44, v44
	v_sub_f32_e32 v45, v45, v48
	v_add_f32_e32 v50, v142, v50
	v_exp_f32_e32 v45, v45
	v_sub_f32_e32 v46, v46, v48
	v_add_f32_e32 v50, v180, v50
	v_exp_f32_e32 v46, v46
	v_sub_f32_e32 v47, v47, v48
	v_add_f32_e32 v50, v179, v50
	v_exp_f32_e32 v47, v47
	v_add_f32_e32 v50, v44, v50
	v_add_f32_e32 v50, v45, v50
	v_add_f32_e32 v50, v46, v50
	v_add_f32_e32 v178, v47, v50
	v_fmac_f32_e32 v178, v174, v36
	v_cvt_pk_bf16_f32 v36, v49, v37
	v_cvt_pk_bf16_f32 v37, v38, v39
	v_cvt_pk_bf16_f32 v39, v42, v43
	v_cvt_pk_bf16_f32 v42, v44, v45
	v_cvt_pk_bf16_f32 v43, v46, v47
	ds_read_b64_tr_b16 v[44:45], v173 offset:4608
	ds_read_b64_tr_b16 v[46:47], v173 offset:5760
	v_cvt_pk_bf16_f32 v38, v40, v41
	v_cvt_pk_bf16_f32 v40, v51, v142
	v_cvt_pk_bf16_f32 v41, v180, v179
	s_waitcnt lgkmcnt(0)
	v_mfma_f32_32x32x16_bf16 v[20:35], v[44:47], v[36:39], v[20:35]
	ds_read_b64_tr_b16 v[44:45], v173 offset:4672
	ds_read_b64_tr_b16 v[46:47], v173 offset:5824
	s_add_i32 s18, s17, 1
	s_cmp_ge_i32 s18, s15
	s_waitcnt lgkmcnt(0)
	v_mfma_f32_32x32x16_bf16 v[4:19], v[44:47], v[36:39], v[4:19]
	ds_read_b64_tr_b16 v[36:37], v173 offset:6912
	ds_read_b64_tr_b16 v[38:39], v173 offset:8064
	s_waitcnt lgkmcnt(0)
	v_mfma_f32_32x32x16_bf16 v[20:35], v[36:39], v[40:43], v[20:35]
	ds_read_b64_tr_b16 v[36:37], v173 offset:6976
	ds_read_b64_tr_b16 v[38:39], v173 offset:8128
	s_waitcnt lgkmcnt(0)
	v_mfma_f32_32x32x16_bf16 v[4:19], v[36:39], v[40:43], v[4:19]
	s_cbranch_scc1 .LBB0_865
	s_add_i32 s18, s17, 3
	s_waitcnt vmcnt(8)
	s_cmp_eq_u32 s32, 2
	s_cbranch_scc1 .Latw_pb_2
	s_waitcnt vmcnt(0)
.Latw_pb_2:
	s_cmp_ge_i32 s18, s15
	ds_write_b128 v177, v[92:95]
	ds_write_b128 v177, v[96:99] offset:4608
	ds_write_b128 v177, v[108:111] offset:1152
	ds_write_b128 v177, v[112:115] offset:5760
	ds_write_b128 v177, v[116:119] offset:2304
	ds_write_b128 v177, v[120:123] offset:6912
	ds_write_b128 v177, v[124:127] offset:3456
	ds_write_b128 v177, v[128:131] offset:8064
	s_mov_b32 s32, 0
	s_cbranch_scc1 .LBB0_862
	s_cmp_gt_i32 s18, s12
	s_cselect_b32 s19, s13, s11
	s_cselect_b32 s18, 4, 2
	s_add_i32 s19, s19, s17
	s_lshl_b32 s19, s19, 5
	s_addk_i32 s19, 0x60
	s_lshl_b32 s22, -1, s18
	v_or_b32_e32 v40, s19, v144
	s_andn2_b32 s22, s7, s22
	v_lshlrev_b32_e32 v36, s18, v40
	v_add_u32_e32 v36, s22, v36
	v_min_i32_e32 v36, 0x7ff, v36
	v_ashrrev_i32_e32 v37, 31, v36
	v_lshlrev_b64 v[36:37], 11, v[36:37]
	v_lshl_add_u64 v[36:37], v[36:37], 0, v[140:141]
	v_lshl_add_u64 v[38:39], s[0:1], 0, v[36:37]
	v_lshl_add_u64 v[36:37], s[72:73], 0, v[36:37]
	global_load_dwordx4 v[92:95], v[38:39], off
	global_load_dwordx4 v[96:99], v[36:37], off
	v_or_b32_e32 v36, 8, v40
	v_lshlrev_b32_e32 v36, s18, v36
	v_add_u32_e32 v36, s22, v36
	v_min_i32_e32 v36, 0x7ff, v36
	v_ashrrev_i32_e32 v37, 31, v36
	v_lshlrev_b64 v[36:37], 11, v[36:37]
	v_lshl_add_u64 v[36:37], v[36:37], 0, v[140:141]
	v_lshl_add_u64 v[38:39], s[0:1], 0, v[36:37]
	v_lshl_add_u64 v[36:37], s[72:73], 0, v[36:37]
	global_load_dwordx4 v[108:111], v[38:39], off
	global_load_dwordx4 v[112:115], v[36:37], off
	v_or_b32_e32 v36, 16, v40
	v_lshlrev_b32_e32 v36, s18, v36
	v_add_u32_e32 v36, s22, v36
	v_min_i32_e32 v36, 0x7ff, v36
	v_ashrrev_i32_e32 v37, 31, v36
	v_lshlrev_b64 v[36:37], 11, v[36:37]
	v_lshl_add_u64 v[36:37], v[36:37], 0, v[140:141]
	v_lshl_add_u64 v[38:39], s[0:1], 0, v[36:37]
	v_lshl_add_u64 v[36:37], s[72:73], 0, v[36:37]
	global_load_dwordx4 v[116:119], v[38:39], off
	global_load_dwordx4 v[120:123], v[36:37], off
	v_or_b32_e32 v36, 24, v40
	v_lshlrev_b32_e32 v36, s18, v36
	v_add_u32_e32 v36, s22, v36
	v_min_i32_e32 v36, 0x7ff, v36
	v_ashrrev_i32_e32 v37, 31, v36
	v_lshlrev_b64 v[36:37], 11, v[36:37]
	v_lshl_add_u64 v[36:37], v[36:37], 0, v[140:141]
	v_lshl_add_u64 v[38:39], s[0:1], 0, v[36:37]
	v_lshl_add_u64 v[36:37], s[72:73], 0, v[36:37]
	global_load_dwordx4 v[124:127], v[38:39], off
	global_load_dwordx4 v[128:131], v[36:37], off
	s_mov_b32 s32, 1

.LBB0_879:
	s_add_i32 s23, s24, 2
	s_cmp_ge_i32 s24, s19
	s_cselect_b64 s[10:11], -1, 0
	v_add_u32_e32 v174, v150, v138
	v_add_u32_e32 v176, v150, v143
	v_add_u32_e32 v177, v150, v145
	v_add_u32_e32 v175, v150, v148
	s_and_b64 vcc, exec, s[10:11]
	s_cmp_eq_u32 s32, 1
	s_cbranch_scc0 .Latw_cons_3
	s_waitcnt vmcnt(15)
	ds_write_b128 v174, v[68:71]
	s_waitcnt vmcnt(14)
	ds_write_b128 v174, v[72:75] offset:4608
	s_waitcnt vmcnt(13)
	ds_write_b128 v176, v[76:79]
	s_waitcnt vmcnt(12)
	ds_write_b128 v176, v[80:83] offset:4608
	s_waitcnt vmcnt(11)
	ds_write_b128 v177, v[84:87]
	s_waitcnt vmcnt(10)
	ds_write_b128 v177, v[88:91] offset:4608
	s_waitcnt vmcnt(9)
	ds_write_b128 v175, v[100:103]
	s_waitcnt vmcnt(8)
	ds_write_b128 v175, v[104:107] offset:4608
	s_branch .Latw_pa_3
.Latw_cons_3:
	s_waitcnt vmcnt(7)
	ds_write_b128 v174, v[68:71]
	s_waitcnt vmcnt(6)
	ds_write_b128 v174, v[72:75] offset:4608
	s_waitcnt vmcnt(5)
	ds_write_b128 v176, v[76:79]
	s_waitcnt vmcnt(4)
	ds_write_b128 v176, v[80:83] offset:4608
	s_waitcnt vmcnt(3)
	ds_write_b128 v177, v[84:87]
	s_waitcnt vmcnt(2)
	ds_write_b128 v177, v[88:91] offset:4608
	s_waitcnt vmcnt(1)
	ds_write_b128 v175, v[100:103]
	s_waitcnt vmcnt(0)
	ds_write_b128 v175, v[104:107] offset:4608
.Latw_pa_3:
	s_mov_b32 s32, 0
	s_cbranch_vccnz .LBB0_881
	s_cmp_gt_i32 s23, s17
	s_cselect_b32 s26, s18, s16
	s_cselect_b32 s25, 4, 2
	s_add_i32 s26, s26, s24
	s_lshl_b32 s26, s26, 5
	s_lshl_b32 s27, -1, s25
	v_add3_u32 v40, s26, 64, v149
	s_andn2_b32 s27, s13, s27
	v_lshlrev_b32_e32 v36, s25, v40
	v_add_u32_e32 v36, s27, v36
	v_min_i32_e32 v36, 0x7ff, v36
	v_ashrrev_i32_e32 v37, 31, v36
	v_lshlrev_b64 v[36:37], 11, v[36:37]
	v_lshl_add_u64 v[36:37], v[36:37], 0, v[2:3]
	v_lshl_add_u64 v[38:39], s[0:1], 0, v[36:37]
	v_lshl_add_u64 v[36:37], s[72:73], 0, v[36:37]
	global_load_dwordx4 v[68:71], v[38:39], off
	global_load_dwordx4 v[72:75], v[36:37], off
	v_add_lshl_u32 v36, v40, 8, s25
	v_add_u32_e32 v36, s27, v36
	v_min_i32_e32 v36, 0x7ff, v36
	v_ashrrev_i32_e32 v37, 31, v36
	v_lshlrev_b64 v[36:37], 11, v[36:37]
	v_lshl_add_u64 v[36:37], v[36:37], 0, v[2:3]
	v_lshl_add_u64 v[38:39], s[0:1], 0, v[36:37]
	v_lshl_add_u64 v[36:37], s[72:73], 0, v[36:37]
	global_load_dwordx4 v[76:79], v[38:39], off
	global_load_dwordx4 v[80:83], v[36:37], off
	v_add_lshl_u32 v36, v40, 16, s25
	v_add_u32_e32 v36, s27, v36
	v_min_i32_e32 v36, 0x7ff, v36
	v_ashrrev_i32_e32 v37, 31, v36
	v_lshlrev_b64 v[36:37], 11, v[36:37]
	v_lshl_add_u64 v[36:37], v[36:37], 0, v[2:3]
	v_lshl_add_u64 v[38:39], s[0:1], 0, v[36:37]
	v_lshl_add_u64 v[36:37], s[72:73], 0, v[36:37]
	global_load_dwordx4 v[84:87], v[38:39], off
	global_load_dwordx4 v[88:91], v[36:37], off
	v_add_lshl_u32 v36, v40, 24, s25
	v_add_u32_e32 v36, s27, v36
	v_min_i32_e32 v36, 0x7ff, v36
	v_ashrrev_i32_e32 v37, 31, v36
	v_lshlrev_b64 v[36:37], 11, v[36:37]
	v_lshl_add_u64 v[36:37], v[36:37], 0, v[2:3]
	v_lshl_add_u64 v[38:39], s[0:1], 0, v[36:37]
	v_lshl_add_u64 v[36:37], s[72:73], 0, v[36:37]
	global_load_dwordx4 v[100:103], v[38:39], off
	global_load_dwordx4 v[104:107], v[36:37], off
	s_mov_b32 s32, 2

.LBB0_883:
	v_sub_f32_e32 v49, v173, v48
	v_exp_f32_e32 v49, v49
	v_sub_f32_e32 v37, v37, v48
	v_exp_f32_e32 v37, v37
	v_sub_f32_e32 v38, v38, v48
	v_exp_f32_e32 v38, v38
	v_sub_f32_e32 v39, v39, v48
	v_exp_f32_e32 v39, v39
	v_sub_f32_e32 v40, v40, v48
	v_add_f32_e32 v50, 0, v49
	v_exp_f32_e32 v40, v40
	v_sub_f32_e32 v41, v41, v48
	v_add_f32_e32 v50, v37, v50
	v_exp_f32_e32 v41, v41
	v_sub_f32_e32 v42, v42, v48
	v_add_f32_e32 v50, v38, v50
	v_exp_f32_e32 v42, v42
	v_sub_f32_e32 v43, v43, v48
	v_add_f32_e32 v50, v39, v50
	v_exp_f32_e32 v43, v43
	v_sub_f32_e32 v51, v181, v48
	v_add_f32_e32 v50, v40, v50
	v_exp_f32_e32 v51, v51
	v_sub_f32_e32 v136, v180, v48
	v_add_f32_e32 v50, v41, v50
	v_exp_f32_e32 v136, v136
	v_sub_f32_e32 v173, v179, v48
	v_add_f32_e32 v50, v42, v50
	v_exp_f32_e32 v179, v173
	v_sub_f32_e32 v173, v178, v48
	v_add_f32_e32 v50, v43, v50
	v_exp_f32_e32 v178, v173
	v_sub_f32_e32 v44, v44, v48
	v_add_f32_e32 v50, v51, v50
	v_exp_f32_e32 v44, v44
	v_sub_f32_e32 v45, v45, v48
	v_add_f32_e32 v50, v136, v50
	v_exp_f32_e32 v45, v45
	v_sub_f32_e32 v46, v46, v48
	v_add_f32_e32 v50, v179, v50
	v_exp_f32_e32 v46, v46
	v_sub_f32_e32 v47, v47, v48
	v_add_f32_e32 v50, v178, v50
	v_exp_f32_e32 v47, v47
	v_add_f32_e32 v50, v44, v50
	v_add_f32_e32 v50, v45, v50
	v_add_f32_e32 v50, v46, v50
	v_add_f32_e32 v173, v47, v50
	v_fmac_f32_e32 v173, v171, v36
	v_cvt_pk_bf16_f32 v36, v49, v37
	v_cvt_pk_bf16_f32 v37, v38, v39
	v_cvt_pk_bf16_f32 v39, v42, v43
	v_cvt_pk_bf16_f32 v42, v44, v45
	v_cvt_pk_bf16_f32 v43, v46, v47
	ds_read_b64_tr_b16 v[44:45], v169 offset:4608
	ds_read_b64_tr_b16 v[46:47], v169 offset:5760
	v_cvt_pk_bf16_f32 v38, v40, v41
	v_cvt_pk_bf16_f32 v40, v51, v136
	v_cvt_pk_bf16_f32 v41, v179, v178
	s_waitcnt lgkmcnt(0)
	v_mfma_f32_32x32x16_bf16 v[20:35], v[44:47], v[36:39], v[20:35]
	ds_read_b64_tr_b16 v[44:45], v169 offset:4672
	ds_read_b64_tr_b16 v[46:47], v169 offset:5824
	s_add_i32 s25, s24, 1
	s_cmp_ge_i32 s25, s22
	s_waitcnt lgkmcnt(0)
	v_mfma_f32_32x32x16_bf16 v[4:19], v[44:47], v[36:39], v[4:19]
	ds_read_b64_tr_b16 v[36:37], v169 offset:6912
	ds_read_b64_tr_b16 v[38:39], v169 offset:8064
	s_waitcnt lgkmcnt(0)
	v_mfma_f32_32x32x16_bf16 v[20:35], v[36:39], v[40:43], v[20:35]
	ds_read_b64_tr_b16 v[36:37], v169 offset:6976
	ds_read_b64_tr_b16 v[38:39], v169 offset:8128
	s_waitcnt lgkmcnt(0)
	v_mfma_f32_32x32x16_bf16 v[4:19], v[36:39], v[40:43], v[4:19]
	s_cbranch_scc1 .LBB0_889
	s_add_i32 s25, s24, 3
	s_waitcnt vmcnt(8)
	s_cmp_eq_u32 s32, 2
	s_cbranch_scc1 .Latw_pb_3
	s_waitcnt vmcnt(0)
.Latw_pb_3:
	s_cmp_ge_i32 s25, s22
	ds_write_b128 v174, v[92:95]
	ds_write_b128 v174, v[96:99] offset:4608
	ds_write_b128 v176, v[108:111]
	ds_write_b128 v176, v[112:115] offset:4608
	ds_write_b128 v177, v[116:119]
	ds_write_b128 v177, v[120:123] offset:4608
	ds_write_b128 v175, v[124:127]
	ds_write_b128 v175, v[128:131] offset:4608
	s_mov_b32 s32, 0
	s_cbranch_scc1 .LBB0_886
	s_cmp_gt_i32 s25, s17
	s_cselect_b32 s26, s18, s16
	s_cselect_b32 s25, 4, 2
	s_add_i32 s26, s26, s24
	s_lshl_b32 s26, s26, 5
	s_addk_i32 s26, 0x60
	s_lshl_b32 s27, -1, s25
	v_add_u32_e32 v40, s26, v149
	s_andn2_b32 s27, s13, s27
	v_lshlrev_b32_e32 v36, s25, v40
	v_add_u32_e32 v36, s27, v36
	v_min_i32_e32 v36, 0x7ff, v36
	v_ashrrev_i32_e32 v37, 31, v36
	v_lshlrev_b64 v[36:37], 11, v[36:37]
	v_lshl_add_u64 v[36:37], v[36:37], 0, v[2:3]
	v_lshl_add_u64 v[38:39], s[0:1], 0, v[36:37]
	v_lshl_add_u64 v[36:37], s[72:73], 0, v[36:37]
	global_load_dwordx4 v[92:95], v[38:39], off
	global_load_dwordx4 v[96:99], v[36:37], off
	v_add_lshl_u32 v36, v40, 8, s25
	v_add_u32_e32 v36, s27, v36
	v_min_i32_e32 v36, 0x7ff, v36
	v_ashrrev_i32_e32 v37, 31, v36
	v_lshlrev_b64 v[36:37], 11, v[36:37]
	v_lshl_add_u64 v[36:37], v[36:37], 0, v[2:3]
	v_lshl_add_u64 v[38:39], s[0:1], 0, v[36:37]
	v_lshl_add_u64 v[36:37], s[72:73], 0, v[36:37]
	global_load_dwordx4 v[108:111], v[38:39], off
	global_load_dwordx4 v[112:115], v[36:37], off
	v_add_lshl_u32 v36, v40, 16, s25
	v_add_u32_e32 v36, s27, v36
	v_min_i32_e32 v36, 0x7ff, v36
	v_ashrrev_i32_e32 v37, 31, v36
	v_lshlrev_b64 v[36:37], 11, v[36:37]
	v_lshl_add_u64 v[36:37], v[36:37], 0, v[2:3]
	v_lshl_add_u64 v[38:39], s[0:1], 0, v[36:37]
	v_lshl_add_u64 v[36:37], s[72:73], 0, v[36:37]
	global_load_dwordx4 v[116:119], v[38:39], off
	global_load_dwordx4 v[120:123], v[36:37], off
	v_add_lshl_u32 v36, v40, 24, s25
	v_add_u32_e32 v36, s27, v36
	v_min_i32_e32 v36, 0x7ff, v36
	v_ashrrev_i32_e32 v37, 31, v36
	v_lshlrev_b64 v[36:37], 11, v[36:37]
	v_lshl_add_u64 v[36:37], v[36:37], 0, v[2:3]
	v_lshl_add_u64 v[38:39], s[0:1], 0, v[36:37]
	v_lshl_add_u64 v[36:37], s[72:73], 0, v[36:37]
	global_load_dwordx4 v[124:127], v[38:39], off
	global_load_dwordx4 v[128:131], v[36:37], off
	s_mov_b32 s32, 1
